# v68 variant: no static priority raise; instead s_setprio 1 only across the MFMA-free middle of each KV step (set after the last QK^T MFMA, cleared at the start of the exp section)
# speedup vs baseline: 1.0076x; 1.0062x over previous
.LBB0_1588:
	s_or_b64 exec, exec, s[0:1]
	v_cmp_gt_u32_e32 vcc, 0x100, v229
	s_cbranch_vccnz .Latt_prio_done
.Latt_prio_done:
	s_mov_b64 s[0:1], s[74:75]
	s_waitcnt lgkmcnt(0)
	v_mov_b32_e32 v0, v229
	s_mov_b32 s33, s2
	s_and_b64 vcc, exec, s[84:85]
	s_barrier
	s_cbranch_vccnz .LBB0_1590
	s_cmpk_gt_i32 s33, 0x1ff
	s_cbranch_scc0 .LBB0_1591
	s_branch .LBB0_1678

.LBB0_1604:
	v_add_u32_e32 v0, s22, v244
	ds_read_b64_tr_b16 v[208:209], v0 offset:24576
	ds_read_b64_tr_b16 v[210:211], v0 offset:25088
	s_waitcnt lgkmcnt(9)
	v_mfma_f32_32x32x16_bf16 v[112:127], v[204:207], v[172:175], 0
	v_add_f32_e32 v2, v87, v88
	v_cvt_pk_bf16_f32 v156, v96, v97
	v_cvt_pk_bf16_f32 v157, v98, v99
	ds_read_b64_tr_b16 v[204:205], v0 offset:28672
	ds_read_b64_tr_b16 v[206:207], v0 offset:29184
	v_add_f32_e32 v2, v89, v2
	v_cvt_pk_bf16_f32 v158, v100, v101
	v_cvt_pk_bf16_f32 v159, v102, v103
	s_waitcnt lgkmcnt(10)
	v_mfma_f32_32x32x16_bf16 v[128:143], v[200:203], v[172:175], 0
	ds_read_b64_tr_b16 v[10:11], v0 offset:25600
	ds_read_b64_tr_b16 v[12:13], v0 offset:26112
	s_waitcnt lgkmcnt(11)
	v_mfma_f32_32x32x16_bf16 v[112:127], v[196:199], v[168:171], v[112:127]
	v_add_f32_e32 v2, v90, v2
	v_cvt_pk_bf16_f32 v152, v104, v105
	v_cvt_pk_bf16_f32 v153, v106, v107
	ds_read_b64_tr_b16 v[6:7], v0 offset:29696
	ds_read_b64_tr_b16 v[8:9], v0 offset:30208
	v_add_f32_e32 v14, v91, v2
	v_cvt_pk_bf16_f32 v154, v108, v109
	v_cvt_pk_bf16_f32 v155, v110, v111
	s_waitcnt lgkmcnt(12)
	v_mfma_f32_32x32x16_bf16 v[128:143], v[192:195], v[168:171], v[128:143]
	ds_read_b64_tr_b16 v[2:3], v0 offset:26624
	ds_read_b64_tr_b16 v[4:5], v0 offset:27136
	s_waitcnt lgkmcnt(13)
	v_mfma_f32_32x32x16_bf16 v[112:127], v[188:191], v[164:167], v[112:127]
	v_add_f32_e32 v14, v92, v14
	v_cvt_pk_bf16_f32 v148, v80, v81
	v_cvt_pk_bf16_f32 v149, v82, v83
	ds_read_b64_tr_b16 v[196:197], v0 offset:30720
	ds_read_b64_tr_b16 v[198:199], v0 offset:31232
	v_add_f32_e32 v14, v93, v14
	v_cvt_pk_bf16_f32 v150, v84, v85
	v_cvt_pk_bf16_f32 v151, v86, v87
	s_waitcnt lgkmcnt(14)
	v_mfma_f32_32x32x16_bf16 v[128:143], v[184:187], v[164:167], v[128:143]
	ds_read_b64_tr_b16 v[192:193], v0 offset:27648
	ds_read_b64_tr_b16 v[194:195], v0 offset:28160
	s_waitcnt lgkmcnt(14)
	v_mfma_f32_32x32x16_bf16 v[112:127], v[180:183], v[160:163], v[112:127]
	v_add_f32_e32 v14, v94, v14
	v_cvt_pk_bf16_f32 v144, v88, v89
	v_cvt_pk_bf16_f32 v145, v90, v91
	ds_read_b64_tr_b16 v[188:189], v0 offset:31744
	ds_read_b64_tr_b16 v[190:191], v0 offset:32256
	v_add_f32_e32 v96, v95, v14
	v_cvt_pk_bf16_f32 v146, v92, v93
	v_cvt_pk_bf16_f32 v147, v94, v95
	v_mfma_f32_32x32x16_bf16 v[128:143], v[176:179], v[160:163], v[128:143]
	s_setprio 1
	s_nop 2
	v_add_f32_e64 v80, v112, -v228
	v_add_f32_e64 v81, v113, -v228
	v_pk_add_f32 v[98:99], v[114:115], v[228:229] op_sel_hi:[1,0] neg_lo:[0,1] neg_hi:[0,1]
	v_pk_add_f32 v[100:101], v[116:117], v[228:229] op_sel_hi:[1,0] neg_lo:[0,1] neg_hi:[0,1]
	v_pk_add_f32 v[102:103], v[118:119], v[228:229] op_sel_hi:[1,0] neg_lo:[0,1] neg_hi:[0,1]
	v_pk_add_f32 v[104:105], v[120:121], v[228:229] op_sel_hi:[1,0] neg_lo:[0,1] neg_hi:[0,1]
	v_pk_add_f32 v[106:107], v[122:123], v[228:229] op_sel_hi:[1,0] neg_lo:[0,1] neg_hi:[0,1]
	v_pk_add_f32 v[108:109], v[124:125], v[228:229] op_sel_hi:[1,0] neg_lo:[0,1] neg_hi:[0,1]
	v_pk_add_f32 v[110:111], v[126:127], v[228:229] op_sel_hi:[1,0] neg_lo:[0,1] neg_hi:[0,1]
	v_max_f32_e32 v97, v80, v81
	s_add_u32 s30, s16, s10
	v_pk_add_f32 v[14:15], v[128:129], v[228:229] op_sel_hi:[1,0] neg_lo:[0,1] neg_hi:[0,1]
	v_max3_f32 v112, v98, v99, v100
	s_addc_u32 s31, s17, s11
	v_pk_add_f32 v[82:83], v[130:131], v[228:229] op_sel_hi:[1,0] neg_lo:[0,1] neg_hi:[0,1]
	v_max3_f32 v97, v97, v101, v102
	s_add_u32 s22, s30, 0x80000
	v_pk_add_f32 v[84:85], v[132:133], v[228:229] op_sel_hi:[1,0] neg_lo:[0,1] neg_hi:[0,1]
	v_max3_f32 v112, v112, v103, v104
	s_addc_u32 s23, s31, 0
	v_pk_add_f32 v[86:87], v[134:135], v[228:229] op_sel_hi:[1,0] neg_lo:[0,1] neg_hi:[0,1]
	v_max3_f32 v97, v97, v105, v106
	s_add_i32 s24, s29, s57
	v_pk_add_f32 v[88:89], v[136:137], v[228:229] op_sel_hi:[1,0] neg_lo:[0,1] neg_hi:[0,1]
	v_max3_f32 v112, v112, v107, v108
	s_add_u32 s62, s18, s10
	v_pk_add_f32 v[90:91], v[138:139], v[228:229] op_sel_hi:[1,0] neg_lo:[0,1] neg_hi:[0,1]
	v_max3_f32 v97, v97, v109, v110
	s_addc_u32 s63, s19, s11
	v_pk_add_f32 v[92:93], v[140:141], v[228:229] op_sel_hi:[1,0] neg_lo:[0,1] neg_hi:[0,1]
	v_max3_f32 v112, v112, v111, v14
	v_pk_add_f32 v[94:95], v[142:143], v[228:229] op_sel_hi:[1,0] neg_lo:[0,1] neg_hi:[0,1]
	v_max3_f32 v97, v97, v15, v82
	v_max3_f32 v112, v112, v83, v84
	v_max3_f32 v97, v97, v85, v86
	v_max3_f32 v112, v112, v87, v88
	v_max3_f32 v97, v97, v89, v90
	v_max3_f32 v112, v112, v91, v92
	v_max3_f32 v97, v97, v94, v95
	s_mov_b32 s25, m0
	s_mov_b32 m0, s24
	s_nop 0
	global_load_lds_dwordx4 v241, s[22:23]
	s_mov_b32 m0, s25
	s_add_u32 s22, s62, 0x40000
	v_add_f32_e32 v116, v224, v96
	v_max3_f32 v96, v97, v93, v112
	s_addc_u32 s23, s63, 0
	s_add_i32 s24, s28, s58
	v_mov_b32_e32 v97, v96
	s_add_u32 s64, s20, s10
	s_nop 0
	v_permlane32_swap_b32_e32 v96, v97
	s_addc_u32 s65, s21, s11
	s_mov_b32 s25, m0
	s_mov_b32 m0, s24
	s_nop 0
	global_load_lds_dwordx4 v242, s[22:23]
	s_mov_b32 m0, s25
	s_add_u32 s22, s64, 0x40000
	v_max_f32_e32 v96, v96, v97
	s_addc_u32 s23, s65, 0
	s_add_i32 s24, s28, s59
	s_mov_b32 s25, m0
	s_mov_b32 m0, s24
	s_nop 0
	global_load_lds_dwordx4 v242, s[22:23]
	s_mov_b32 m0, s25
	v_cmp_lt_f32_e32 vcc, s35, v96
	s_cmp_lg_u64 vcc, 0
	s_cselect_b64 s[22:23], -1, 0
	s_cbranch_vccnz .LBB0_1612
.LBB0_1605:
	s_setprio 0
	s_waitcnt lgkmcnt(14)
	v_mfma_f32_32x32x16_bf16 v[64:79], v[156:159], v[208:211], v[64:79]
	v_exp_f32_e32 v96, v80
	v_exp_f32_e32 v97, v81
	v_mov_b32_e32 v80, 0
	ds_read_b64_tr_b16 v[118:119], v0 offset:49152
	ds_read_b64_tr_b16 v[120:121], v0 offset:49664
	s_waitcnt lgkmcnt(14)
	v_mfma_f32_32x32x16_bf16 v[48:63], v[156:159], v[204:207], v[48:63]
	v_add_f32_e32 v80, v80, v96
	v_exp_f32_e32 v98, v98
	v_exp_f32_e32 v99, v99
	v_add_f32_e32 v80, 0, v80
	ds_read_b64_tr_b16 v[122:123], v0 offset:53248
	ds_read_b64_tr_b16 v[124:125], v0 offset:53760
	v_add_u32_e32 v81, s28, v243
	ds_read_b128 v[112:115], v81
	ds_read_b128 v[128:131], v81 offset:512
	s_waitcnt lgkmcnt(14)
	v_mfma_f32_32x32x16_bf16 v[64:79], v[152:155], v[10:13], v[64:79]
	v_add_f32_e32 v80, v80, v97
	v_exp_f32_e32 v100, v100
	v_exp_f32_e32 v101, v101
	v_add_f32_e32 v80, 0, v80
	ds_read_b64_tr_b16 v[132:133], v0 offset:50176
	ds_read_b64_tr_b16 v[134:135], v0 offset:50688
	ds_read_b128 v[184:187], v81 offset:2048
	ds_read_b128 v[176:179], v81 offset:2560
	v_mfma_f32_32x32x16_bf16 v[48:63], v[152:155], v[6:9], v[48:63]
	v_add_f32_e32 v10, v80, v98
	v_exp_f32_e32 v102, v102
	v_exp_f32_e32 v103, v103
	v_add_f32_e32 v10, 0, v10
	ds_read_b64_tr_b16 v[136:137], v0 offset:54272
	ds_read_b64_tr_b16 v[138:139], v0 offset:54784
	ds_read_b128 v[180:183], v81 offset:4096
	ds_read_b128 v[6:9], v81 offset:4608
	s_waitcnt lgkmcnt(14)
	v_mfma_f32_32x32x16_bf16 v[64:79], v[148:151], v[2:5], v[64:79]
	v_add_f32_e32 v10, v10, v99
	v_exp_f32_e32 v104, v104
	v_exp_f32_e32 v105, v105
	v_add_f32_e32 v80, 0, v10
	ds_read_b64_tr_b16 v[140:141], v0 offset:51200
	ds_read_b64_tr_b16 v[142:143], v0 offset:51712
	ds_read_b128 v[10:13], v81 offset:6144
	ds_read_b128 v[2:5], v81 offset:6656
	v_mfma_f32_32x32x16_bf16 v[48:63], v[148:151], v[196:199], v[48:63]
	v_add_f32_e32 v80, v80, v100
	v_exp_f32_e32 v106, v106
	v_exp_f32_e32 v107, v107
	v_add_f32_e32 v80, 0, v80
	ds_read_b64_tr_b16 v[196:197], v0 offset:55296
	ds_read_b64_tr_b16 v[198:199], v0 offset:55808
	v_mfma_f32_32x32x16_bf16 v[64:79], v[144:147], v[192:195], v[64:79]
	v_add_f32_e32 v80, v80, v101
	v_exp_f32_e32 v108, v108
	v_exp_f32_e32 v109, v109
	v_add_f32_e32 v80, 0, v80
	ds_read_b64_tr_b16 v[192:193], v0 offset:52224
	ds_read_b64_tr_b16 v[194:195], v0 offset:52736
	v_mfma_f32_32x32x16_bf16 v[48:63], v[144:147], v[188:191], v[48:63]
	v_add_f32_e32 v80, v80, v102
	v_exp_f32_e32 v110, v110
	v_exp_f32_e32 v111, v111
	v_add_f32_e32 v117, 0, v80
	ds_read_b64_tr_b16 v[188:189], v0 offset:56320
	ds_read_b64_tr_b16 v[190:191], v0 offset:56832
	s_waitcnt lgkmcnt(14)
	v_mfma_f32_32x32x16_bf16 v[32:47], v[156:159], v[118:121], v[32:47]
	v_add_f32_e32 v0, v117, v103
	v_exp_f32_e32 v80, v14
	v_exp_f32_e32 v81, v15
	v_add_f32_e32 v0, v104, v0
	v_mfma_f32_32x32x16_bf16 v[16:31], v[156:159], v[122:125], v[16:31]
	v_add_f32_e32 v0, v105, v0
	v_exp_f32_e32 v82, v82
	v_exp_f32_e32 v83, v83
	v_add_f32_e32 v0, v106, v0
	v_mfma_f32_32x32x16_bf16 v[32:47], v[152:155], v[132:135], v[32:47]
	v_add_f32_e32 v0, v107, v0
	v_exp_f32_e32 v84, v84
	v_exp_f32_e32 v85, v85
	v_add_f32_e32 v0, v108, v0
	s_waitcnt lgkmcnt(12)
	v_mfma_f32_32x32x16_bf16 v[16:31], v[152:155], v[136:139], v[16:31]
	v_add_f32_e32 v0, v109, v0
	v_exp_f32_e32 v86, v86
	v_exp_f32_e32 v87, v87
	v_add_f32_e32 v0, v110, v0
	s_waitcnt lgkmcnt(8)
	v_mfma_f32_32x32x16_bf16 v[32:47], v[148:151], v[140:143], v[32:47]
	v_add_f32_e32 v0, v111, v0
	v_exp_f32_e32 v88, v88
	v_exp_f32_e32 v89, v89
	v_add_f32_e32 v0, v0, v80
	s_waitcnt lgkmcnt(4)
	v_mfma_f32_32x32x16_bf16 v[16:31], v[148:151], v[196:199], v[16:31]
	v_add_f32_e32 v0, v0, v81
	v_exp_f32_e32 v90, v90
	v_exp_f32_e32 v91, v91
	v_add_f32_e32 v0, v82, v0
	s_waitcnt lgkmcnt(2)
	v_mfma_f32_32x32x16_bf16 v[32:47], v[144:147], v[192:195], v[32:47]
	v_add_f32_e32 v0, v0, v83
	v_exp_f32_e32 v92, v92
	v_exp_f32_e32 v93, v93
	v_add_f32_e32 v0, v84, v0
	s_waitcnt lgkmcnt(0)
	v_mfma_f32_32x32x16_bf16 v[16:31], v[144:147], v[188:191], v[16:31]
	v_add_f32_e32 v0, v0, v85
	v_exp_f32_e32 v94, v94
	v_exp_f32_e32 v95, v95
	v_add_f32_e32 v14, v86, v0
	s_waitcnt vmcnt(3) lgkmcnt(0)
	s_barrier
	s_andn2_b64 vcc, exec, s[22:23]
	v_add_u32_e32 v0, s56, v245
	s_cbranch_vccnz .LBB0_1607
	s_waitcnt lgkmcnt(0)
	ds_read_b128 v[118:121], v0 offset:96
	ds_read_b128 v[122:125], v0 offset:64
	ds_read_b128 v[132:135], v0 offset:32
	ds_read_b128 v[136:139], v0
	s_waitcnt lgkmcnt(3)
	v_pk_mul_f32 v[76:77], v[76:77], v[118:119]
	s_waitcnt lgkmcnt(2)
	v_pk_mul_f32 v[72:73], v[72:73], v[122:123]
	s_waitcnt lgkmcnt(1)
	v_pk_mul_f32 v[68:69], v[68:69], v[132:133]
	v_pk_mul_f32 v[78:79], v[78:79], v[120:121]
	v_pk_mul_f32 v[74:75], v[74:75], v[124:125]
	v_pk_mul_f32 v[70:71], v[70:71], v[134:135]
	s_waitcnt lgkmcnt(0)
	v_pk_mul_f32 v[66:67], v[66:67], v[138:139]
	v_pk_mul_f32 v[64:65], v[64:65], v[136:137]
	v_pk_mul_f32 v[60:61], v[60:61], v[118:119]
	v_pk_mul_f32 v[56:57], v[56:57], v[122:123]
	v_pk_mul_f32 v[52:53], v[52:53], v[132:133]
	v_pk_mul_f32 v[62:63], v[62:63], v[120:121]
	v_pk_mul_f32 v[58:59], v[58:59], v[124:125]
	v_pk_mul_f32 v[54:55], v[54:55], v[134:135]
	v_pk_mul_f32 v[50:51], v[50:51], v[138:139]
	v_pk_mul_f32 v[48:49], v[48:49], v[136:137]
	v_pk_mul_f32 v[44:45], v[44:45], v[118:119]
	v_pk_mul_f32 v[40:41], v[40:41], v[122:123]
	v_pk_mul_f32 v[36:37], v[36:37], v[132:133]
	v_pk_mul_f32 v[46:47], v[46:47], v[120:121]
	v_pk_mul_f32 v[42:43], v[42:43], v[124:125]
	v_pk_mul_f32 v[38:39], v[38:39], v[134:135]
	v_pk_mul_f32 v[34:35], v[34:35], v[138:139]
	v_pk_mul_f32 v[32:33], v[32:33], v[136:137]
	v_pk_mul_f32 v[28:29], v[28:29], v[118:119]
	v_pk_mul_f32 v[24:25], v[24:25], v[122:123]
	v_pk_mul_f32 v[20:21], v[20:21], v[132:133]
	v_pk_mul_f32 v[30:31], v[30:31], v[120:121]
	v_pk_mul_f32 v[26:27], v[26:27], v[124:125]
	v_pk_mul_f32 v[22:23], v[22:23], v[134:135]
	v_pk_mul_f32 v[18:19], v[18:19], v[138:139]
	v_pk_mul_f32 v[16:17], v[16:17], v[136:137]
.LBB0_1607:
	s_add_i32 s22, s28, 0x2000
	s_cmpk_lg_i32 s28, 0x4000
	s_cselect_b32 s61, s22, 0
	v_add_f32_e32 v15, v116, v14
	v_add_u32_e32 v14, s29, v244
	ds_read_b64_tr_b16 v[196:197], v14 offset:24576
	ds_read_b64_tr_b16 v[198:199], v14 offset:25088
	v_add_f32_e32 v132, v87, v88
	v_cvt_pk_bf16_f32 v156, v96, v97
	v_cvt_pk_bf16_f32 v157, v98, v99
	v_mfma_f32_32x32x16_bf16 v[112:127], v[112:115], v[172:175], 0
	ds_read_b64_tr_b16 v[192:193], v14 offset:28672
	ds_read_b64_tr_b16 v[194:195], v14 offset:29184
	v_add_f32_e32 v96, v89, v132
	v_cvt_pk_bf16_f32 v158, v100, v101
	v_cvt_pk_bf16_f32 v159, v102, v103
	v_mfma_f32_32x32x16_bf16 v[128:143], v[128:131], v[172:175], 0
	ds_read_b64_tr_b16 v[188:189], v14 offset:25600
	ds_read_b64_tr_b16 v[190:191], v14 offset:26112
	v_add_f32_e32 v96, v90, v96
	v_cvt_pk_bf16_f32 v152, v104, v105
	v_cvt_pk_bf16_f32 v153, v106, v107
	v_mfma_f32_32x32x16_bf16 v[112:127], v[184:187], v[168:171], v[112:127]
	ds_read_b64_tr_b16 v[184:185], v14 offset:29696
	ds_read_b64_tr_b16 v[186:187], v14 offset:30208
	v_add_f32_e32 v96, v91, v96
	v_cvt_pk_bf16_f32 v154, v108, v109
	v_cvt_pk_bf16_f32 v155, v110, v111
	v_mfma_f32_32x32x16_bf16 v[128:143], v[176:179], v[168:171], v[128:143]
	ds_read_b64_tr_b16 v[176:177], v14 offset:26624
	ds_read_b64_tr_b16 v[178:179], v14 offset:27136
	v_add_f32_e32 v96, v92, v96
	v_cvt_pk_bf16_f32 v148, v80, v81
	v_cvt_pk_bf16_f32 v149, v82, v83
	v_mfma_f32_32x32x16_bf16 v[112:127], v[180:183], v[164:167], v[112:127]
	ds_read_b64_tr_b16 v[212:213], v14 offset:30720
	ds_read_b64_tr_b16 v[214:215], v14 offset:31232
	v_add_f32_e32 v80, v93, v96
	v_cvt_pk_bf16_f32 v150, v84, v85
	v_cvt_pk_bf16_f32 v151, v86, v87
	v_mfma_f32_32x32x16_bf16 v[128:143], v[6:9], v[164:167], v[128:143]
	ds_read_b64_tr_b16 v[208:209], v14 offset:27648
	ds_read_b64_tr_b16 v[210:211], v14 offset:28160
	v_add_f32_e32 v80, v94, v80
	v_cvt_pk_bf16_f32 v144, v88, v89
	v_cvt_pk_bf16_f32 v145, v90, v91
	v_mfma_f32_32x32x16_bf16 v[112:127], v[10:13], v[160:163], v[112:127]
	ds_read_b64_tr_b16 v[6:7], v14 offset:31744
	ds_read_b64_tr_b16 v[8:9], v14 offset:32256
	v_add_f32_e32 v10, v95, v80
	v_cvt_pk_bf16_f32 v146, v92, v93
	v_cvt_pk_bf16_f32 v147, v94, v95
	v_mfma_f32_32x32x16_bf16 v[128:143], v[2:5], v[160:163], v[128:143]
	s_setprio 1
	s_nop 5
	v_add_f32_e64 v4, v112, -v228
	v_add_f32_e64 v5, v113, -v228
	v_pk_add_f32 v[98:99], v[114:115], v[228:229] op_sel_hi:[1,0] neg_lo:[0,1] neg_hi:[0,1]
	v_pk_add_f32 v[100:101], v[116:117], v[228:229] op_sel_hi:[1,0] neg_lo:[0,1] neg_hi:[0,1]
	v_pk_add_f32 v[102:103], v[118:119], v[228:229] op_sel_hi:[1,0] neg_lo:[0,1] neg_hi:[0,1]
	v_pk_add_f32 v[104:105], v[120:121], v[228:229] op_sel_hi:[1,0] neg_lo:[0,1] neg_hi:[0,1]
	v_pk_add_f32 v[106:107], v[122:123], v[228:229] op_sel_hi:[1,0] neg_lo:[0,1] neg_hi:[0,1]
	v_pk_add_f32 v[108:109], v[124:125], v[228:229] op_sel_hi:[1,0] neg_lo:[0,1] neg_hi:[0,1]
	v_pk_add_f32 v[110:111], v[126:127], v[228:229] op_sel_hi:[1,0] neg_lo:[0,1] neg_hi:[0,1]
	v_max_f32_e32 v11, v4, v5
	s_add_u32 s22, s30, 0xa0000
	v_pk_add_f32 v[2:3], v[128:129], v[228:229] op_sel_hi:[1,0] neg_lo:[0,1] neg_hi:[0,1]
	v_max3_f32 v12, v98, v99, v100
	v_pk_add_f32 v[82:83], v[130:131], v[228:229] op_sel_hi:[1,0] neg_lo:[0,1] neg_hi:[0,1]
	v_max3_f32 v11, v11, v101, v102
	v_pk_add_f32 v[84:85], v[132:133], v[228:229] op_sel_hi:[1,0] neg_lo:[0,1] neg_hi:[0,1]
	v_max3_f32 v12, v12, v103, v104
	v_pk_add_f32 v[86:87], v[134:135], v[228:229] op_sel_hi:[1,0] neg_lo:[0,1] neg_hi:[0,1]
	v_max3_f32 v11, v11, v105, v106
	v_pk_add_f32 v[88:89], v[136:137], v[228:229] op_sel_hi:[1,0] neg_lo:[0,1] neg_hi:[0,1]
	v_max3_f32 v12, v12, v107, v108
	v_pk_add_f32 v[90:91], v[138:139], v[228:229] op_sel_hi:[1,0] neg_lo:[0,1] neg_hi:[0,1]
	v_max3_f32 v11, v11, v109, v110
	v_pk_add_f32 v[92:93], v[140:141], v[228:229] op_sel_hi:[1,0] neg_lo:[0,1] neg_hi:[0,1]
	v_max3_f32 v12, v12, v111, v2
	v_pk_add_f32 v[94:95], v[142:143], v[228:229] op_sel_hi:[1,0] neg_lo:[0,1] neg_hi:[0,1]
	v_max3_f32 v11, v11, v3, v82
	v_max3_f32 v12, v12, v83, v84
	v_max3_f32 v11, v11, v85, v86
	v_max3_f32 v12, v12, v87, v88
	v_max3_f32 v11, v11, v89, v90
	v_max3_f32 v12, v12, v91, v92
	v_max3_f32 v11, v11, v94, v95
	v_max3_f32 v11, v11, v93, v12
	s_addc_u32 s23, s31, 0
	s_add_i32 s24, s28, s57
	v_mov_b32_e32 v12, v11
	s_mov_b32 s25, m0
	s_mov_b32 m0, s24
	s_nop 0
	global_load_lds_dwordx4 v241, s[22:23]
	s_mov_b32 m0, s25
	s_add_u32 s22, s62, 0x60000
	s_nop 0
	v_permlane32_swap_b32_e32 v11, v12
	s_addc_u32 s23, s63, 0
	s_add_i32 s24, s61, s58
	s_mov_b32 s25, m0
	s_mov_b32 m0, s24
	s_nop 0
	global_load_lds_dwordx4 v242, s[22:23]
	s_mov_b32 m0, s25
	s_add_u32 s22, s64, 0x60000
	v_max_f32_e32 v11, v11, v12
	s_addc_u32 s23, s65, 0
	s_add_i32 s24, s61, s59
	s_mov_b32 s25, m0
	s_mov_b32 m0, s24
	s_nop 0
	global_load_lds_dwordx4 v242, s[22:23]
	s_mov_b32 m0, s25
	v_cmp_lt_f32_e32 vcc, s35, v11
	s_cmp_lg_u64 vcc, 0
	v_add_f32_e32 v10, v15, v10
	s_cselect_b64 s[22:23], -1, 0
	s_cbranch_vccnz .LBB0_1615
.LBB0_1608:
	s_setprio 0
	s_waitcnt lgkmcnt(14)
	v_mfma_f32_32x32x16_bf16 v[64:79], v[156:159], v[196:199], v[64:79]
	v_exp_f32_e32 v96, v4
	v_exp_f32_e32 v97, v5
	v_mov_b32_e32 v4, 0
	ds_read_b64_tr_b16 v[112:113], v14 offset:49152
	ds_read_b64_tr_b16 v[114:115], v14 offset:49664
	s_waitcnt lgkmcnt(14)
	v_mfma_f32_32x32x16_bf16 v[48:63], v[156:159], v[192:195], v[48:63]
	v_add_f32_e32 v4, v4, v96
	v_exp_f32_e32 v98, v98
	v_exp_f32_e32 v99, v99
	v_add_f32_e32 v4, 0, v4
	ds_read_b64_tr_b16 v[116:117], v14 offset:53248
	ds_read_b64_tr_b16 v[118:119], v14 offset:53760
	v_add_u32_e32 v5, s61, v243
	ds_read_b128 v[204:207], v5
	ds_read_b128 v[200:203], v5 offset:512
	s_waitcnt lgkmcnt(14)
	v_mfma_f32_32x32x16_bf16 v[64:79], v[152:155], v[188:191], v[64:79]
	v_add_f32_e32 v4, v4, v97
	v_exp_f32_e32 v100, v100
	v_exp_f32_e32 v101, v101
	v_add_f32_e32 v4, 0, v4
	ds_read_b64_tr_b16 v[120:121], v14 offset:50176
	ds_read_b64_tr_b16 v[122:123], v14 offset:50688
	ds_read_b128 v[196:199], v5 offset:2048
	ds_read_b128 v[192:195], v5 offset:2560
	v_mfma_f32_32x32x16_bf16 v[48:63], v[152:155], v[184:187], v[48:63]
	v_add_f32_e32 v4, v4, v98
	v_exp_f32_e32 v102, v102
	v_exp_f32_e32 v103, v103
	v_add_f32_e32 v4, 0, v4
	ds_read_b64_tr_b16 v[124:125], v14 offset:54272
	ds_read_b64_tr_b16 v[126:127], v14 offset:54784
	ds_read_b128 v[188:191], v5 offset:4096
	ds_read_b128 v[184:187], v5 offset:4608
	s_waitcnt lgkmcnt(14)
	v_mfma_f32_32x32x16_bf16 v[64:79], v[148:151], v[176:179], v[64:79]
	v_add_f32_e32 v4, v4, v99
	v_exp_f32_e32 v104, v104
	v_exp_f32_e32 v105, v105
	v_add_f32_e32 v4, 0, v4
	ds_read_b64_tr_b16 v[128:129], v14 offset:51200
	ds_read_b64_tr_b16 v[130:131], v14 offset:51712
	ds_read_b128 v[180:183], v5 offset:6144
	ds_read_b128 v[176:179], v5 offset:6656
	v_mfma_f32_32x32x16_bf16 v[48:63], v[148:151], v[212:215], v[48:63]
	v_add_f32_e32 v4, v4, v100
	v_exp_f32_e32 v106, v106
	v_exp_f32_e32 v107, v107
	v_add_f32_e32 v4, 0, v4
	ds_read_b64_tr_b16 v[132:133], v14 offset:55296
	ds_read_b64_tr_b16 v[134:135], v14 offset:55808
	v_mfma_f32_32x32x16_bf16 v[64:79], v[144:147], v[208:211], v[64:79]
	v_add_f32_e32 v4, v4, v101
	v_exp_f32_e32 v108, v108
	v_exp_f32_e32 v109, v109
	v_add_f32_e32 v4, 0, v4
	ds_read_b64_tr_b16 v[136:137], v14 offset:52224
	ds_read_b64_tr_b16 v[138:139], v14 offset:52736
	v_mfma_f32_32x32x16_bf16 v[48:63], v[144:147], v[6:9], v[48:63]
	v_add_f32_e32 v4, v4, v102
	v_exp_f32_e32 v110, v110
	v_exp_f32_e32 v111, v111
	v_add_f32_e32 v11, 0, v4
	ds_read_b64_tr_b16 v[4:5], v14 offset:56320
	ds_read_b64_tr_b16 v[6:7], v14 offset:56832
	s_waitcnt lgkmcnt(14)
	v_mfma_f32_32x32x16_bf16 v[32:47], v[156:159], v[112:115], v[32:47]
	v_exp_f32_e32 v80, v2
	v_add_f32_e32 v2, v11, v103
	v_exp_f32_e32 v81, v3
	v_add_f32_e32 v2, v104, v2
	v_mfma_f32_32x32x16_bf16 v[16:31], v[156:159], v[116:119], v[16:31]
	v_add_f32_e32 v2, v105, v2
	v_exp_f32_e32 v82, v82
	v_exp_f32_e32 v83, v83
	v_add_f32_e32 v2, v106, v2
	v_mfma_f32_32x32x16_bf16 v[32:47], v[152:155], v[120:123], v[32:47]
	v_add_f32_e32 v2, v107, v2
	v_exp_f32_e32 v84, v84
	v_exp_f32_e32 v85, v85
	v_add_f32_e32 v2, v108, v2
	s_waitcnt lgkmcnt(12)
	v_mfma_f32_32x32x16_bf16 v[16:31], v[152:155], v[124:127], v[16:31]
	v_add_f32_e32 v2, v109, v2
	v_exp_f32_e32 v86, v86
	v_exp_f32_e32 v87, v87
	v_add_f32_e32 v2, v110, v2
	s_waitcnt lgkmcnt(8)
	v_mfma_f32_32x32x16_bf16 v[32:47], v[148:151], v[128:131], v[32:47]
	v_add_f32_e32 v2, v111, v2
	v_exp_f32_e32 v88, v88
	v_exp_f32_e32 v89, v89
	v_add_f32_e32 v2, v2, v80
	s_waitcnt lgkmcnt(4)
	v_mfma_f32_32x32x16_bf16 v[16:31], v[148:151], v[132:135], v[16:31]
	v_add_f32_e32 v2, v2, v81
	v_exp_f32_e32 v90, v90
	v_exp_f32_e32 v91, v91
	v_add_f32_e32 v2, v82, v2
	s_waitcnt lgkmcnt(2)
	v_mfma_f32_32x32x16_bf16 v[32:47], v[144:147], v[136:139], v[32:47]
	v_add_f32_e32 v2, v2, v83
	v_exp_f32_e32 v92, v92
	v_exp_f32_e32 v93, v93
	v_add_f32_e32 v2, v84, v2
	s_waitcnt lgkmcnt(0)
	v_mfma_f32_32x32x16_bf16 v[16:31], v[144:147], v[4:7], v[16:31]
	v_add_f32_e32 v2, v2, v85
	v_exp_f32_e32 v94, v94
	v_exp_f32_e32 v95, v95
	v_add_f32_e32 v2, v86, v2
	s_waitcnt vmcnt(3) lgkmcnt(0)
	s_barrier
	s_andn2_b64 vcc, exec, s[22:23]
	s_cbranch_vccnz .LBB0_1610
	s_waitcnt lgkmcnt(0)
	ds_read_b128 v[4:7], v0 offset:96
	ds_read_b128 v[12:15], v0 offset:64
	ds_read_b128 v[112:115], v0 offset:32
	ds_read_b128 v[116:119], v0
	s_waitcnt lgkmcnt(3)
	v_pk_mul_f32 v[76:77], v[76:77], v[4:5]
	s_waitcnt lgkmcnt(2)
	v_pk_mul_f32 v[72:73], v[72:73], v[12:13]
	s_waitcnt lgkmcnt(1)
	v_pk_mul_f32 v[68:69], v[68:69], v[112:113]
	v_pk_mul_f32 v[78:79], v[78:79], v[6:7]
	v_pk_mul_f32 v[74:75], v[74:75], v[14:15]
	v_pk_mul_f32 v[70:71], v[70:71], v[114:115]
	s_waitcnt lgkmcnt(0)
	v_pk_mul_f32 v[66:67], v[66:67], v[118:119]
	v_pk_mul_f32 v[64:65], v[64:65], v[116:117]
	v_pk_mul_f32 v[60:61], v[60:61], v[4:5]
	v_pk_mul_f32 v[56:57], v[56:57], v[12:13]
	v_pk_mul_f32 v[52:53], v[52:53], v[112:113]
	v_pk_mul_f32 v[62:63], v[62:63], v[6:7]
	v_pk_mul_f32 v[58:59], v[58:59], v[14:15]
	v_pk_mul_f32 v[54:55], v[54:55], v[114:115]
	v_pk_mul_f32 v[50:51], v[50:51], v[118:119]
	v_pk_mul_f32 v[48:49], v[48:49], v[116:117]
	v_pk_mul_f32 v[44:45], v[44:45], v[4:5]
	v_pk_mul_f32 v[40:41], v[40:41], v[12:13]
	v_pk_mul_f32 v[36:37], v[36:37], v[112:113]
	v_pk_mul_f32 v[46:47], v[46:47], v[6:7]
	v_pk_mul_f32 v[42:43], v[42:43], v[14:15]
	v_pk_mul_f32 v[38:39], v[38:39], v[114:115]
	v_pk_mul_f32 v[34:35], v[34:35], v[118:119]
	v_pk_mul_f32 v[32:33], v[32:33], v[116:117]
	v_pk_mul_f32 v[28:29], v[28:29], v[4:5]
	v_pk_mul_f32 v[24:25], v[24:25], v[12:13]
	v_pk_mul_f32 v[20:21], v[20:21], v[112:113]
	v_pk_mul_f32 v[30:31], v[30:31], v[6:7]
	v_pk_mul_f32 v[26:27], v[26:27], v[14:15]
	v_pk_mul_f32 v[22:23], v[22:23], v[114:115]
	v_pk_mul_f32 v[18:19], v[18:19], v[118:119]
	v_pk_mul_f32 v[16:17], v[16:17], v[116:117]
